# k39 + seams w_out->FF1 and FF2->gate as row-panel rendezvous, write-through (sc1) stores for cross-WG data instead of an L2 writeback on the arrival path
# speedup vs baseline: 1.0090x; 1.0090x over previous
.LBB0_754:
	s_or_b64 exec, exec, s[12:13]
	v_mov_b32_e32 v128, s22
	v_mov_b32_e32 v129, s23
	s_waitcnt lgkmcnt(0)
	s_barrier
	v_lshl_add_u64 v[152:153], v[200:201], 2, v[128:129]
	ds_read_b32 v158, v209 offset:8192
	v_lshlrev_b64 v[144:145], 10, v[144:145]
	s_add_u32 s8, s18, 0x29d00000
	v_lshl_add_u64 v[160:161], v[144:145], 0, v[200:201]
	s_addc_u32 s9, s19, 0
	v_cvt_pk_bf16_f32 v154, v112, v113
	v_cvt_pk_bf16_f32 v155, v114, v115
	v_cvt_pk_bf16_f32 v156, v116, v117
	v_lshlrev_b64 v[160:161], 1, v[160:161]
	s_waitcnt lgkmcnt(0)
	v_pk_mul_f32 v[114:115], v[114:115], v[158:159] op_sel_hi:[1,0]
	v_pk_mul_f32 v[112:113], v[112:113], v[158:159] op_sel_hi:[1,0]
	v_pk_mul_f32 v[116:117], v[116:117], v[158:159] op_sel_hi:[1,0]
	v_cvt_pk_bf16_f32 v157, v118, v119
	v_lshl_add_u64 v[168:169], s[8:9], 0, v[160:161]
	v_pk_mul_f32 v[118:119], v[118:119], v[158:159] op_sel_hi:[1,0]
	global_store_dwordx4 v[168:169], v[154:157], off nt
	v_lshlrev_b64 v[150:151], 10, v[150:151]
	s_add_u32 s10, s18, 0x12300000
	v_lshl_add_u64 v[162:163], v[150:151], 0, v[200:201]
	s_addc_u32 s11, s19, 0
	v_lshlrev_b64 v[162:163], 1, v[162:163]
	v_lshl_add_u64 v[154:155], s[10:11], 0, v[160:161]
	v_lshl_add_u64 v[170:171], s[8:9], 0, v[162:163]
	v_lshlrev_b64 v[148:149], 10, v[148:149]
	v_lshl_add_u64 v[164:165], v[148:149], 0, v[200:201]
	v_lshl_add_u64 v[156:157], s[10:11], 0, v[162:163]
	v_lshlrev_b64 v[164:165], 1, v[164:165]
	v_lshl_add_u64 v[172:173], s[8:9], 0, v[164:165]
	v_lshlrev_b64 v[146:147], 10, v[146:147]
	v_lshl_add_u64 v[166:167], v[146:147], 0, v[200:201]
	v_lshlrev_b64 v[166:167], 1, v[166:167]
	v_lshl_add_u64 v[160:161], s[10:11], 0, v[164:165]
	v_lshl_add_u64 v[174:175], s[8:9], 0, v[166:167]
	v_pk_mul_f32 v[114:115], v[242:243], v[114:115]
	v_pk_mul_f32 v[112:113], v[240:241], v[112:113]
	v_pk_mul_f32 v[116:117], v[244:245], v[116:117]
	v_pk_mul_f32 v[118:119], v[246:247], v[118:119]
	v_cvt_pk_bf16_f32 v112, v112, v113
	v_cvt_pk_bf16_f32 v113, v114, v115
	v_cvt_pk_bf16_f32 v114, v116, v117
	s_nop 0
	v_cvt_pk_bf16_f32 v115, v118, v119
	ds_read_b32 v116, v209 offset:8256
	global_store_dwordx4 v[154:155], v[112:115], off sc1
	s_waitcnt lgkmcnt(0)
	v_pk_mul_f32 v[118:119], v[126:127], v[116:117] op_sel_hi:[1,0]
	v_cvt_pk_bf16_f32 v112, v120, v121
	v_cvt_pk_bf16_f32 v113, v122, v123
	v_cvt_pk_bf16_f32 v114, v124, v125
	v_cvt_pk_bf16_f32 v115, v126, v127
	global_store_dwordx4 v[170:171], v[112:115], off nt
	v_pk_mul_f32 v[118:119], v[246:247], v[118:119]
	s_nop 0
	v_pk_mul_f32 v[112:113], v[122:123], v[116:117] op_sel_hi:[1,0]
	v_pk_mul_f32 v[114:115], v[120:121], v[116:117] op_sel_hi:[1,0]
	v_pk_mul_f32 v[116:117], v[124:125], v[116:117] op_sel_hi:[1,0]
	v_pk_mul_f32 v[120:121], v[242:243], v[112:113]
	v_pk_mul_f32 v[112:113], v[240:241], v[114:115]
	v_pk_mul_f32 v[114:115], v[244:245], v[116:117]
	v_cvt_pk_bf16_f32 v112, v112, v113
	v_cvt_pk_bf16_f32 v113, v120, v121
	s_nop 0
	v_cvt_pk_bf16_f32 v114, v114, v115
	v_cvt_pk_bf16_f32 v115, v118, v119
	ds_read_b32 v116, v209 offset:8320
	global_store_dwordx4 v[156:157], v[112:115], off sc1
	s_nop 1
	v_cvt_pk_bf16_f32 v112, v104, v105
	v_cvt_pk_bf16_f32 v113, v106, v107
	v_cvt_pk_bf16_f32 v114, v108, v109
	s_waitcnt lgkmcnt(0)
	v_pk_mul_f32 v[106:107], v[106:107], v[116:117] op_sel_hi:[1,0]
	v_pk_mul_f32 v[104:105], v[104:105], v[116:117] op_sel_hi:[1,0]
	v_pk_mul_f32 v[108:109], v[108:109], v[116:117] op_sel_hi:[1,0]
	v_cvt_pk_bf16_f32 v115, v110, v111
	v_pk_mul_f32 v[110:111], v[110:111], v[116:117] op_sel_hi:[1,0]
	v_pk_mul_f32 v[106:107], v[242:243], v[106:107]
	v_pk_mul_f32 v[104:105], v[240:241], v[104:105]
	v_pk_mul_f32 v[108:109], v[244:245], v[108:109]
	global_store_dwordx4 v[172:173], v[112:115], off nt
	v_pk_mul_f32 v[110:111], v[246:247], v[110:111]
	v_cvt_pk_bf16_f32 v104, v104, v105
	v_cvt_pk_bf16_f32 v105, v106, v107
	v_cvt_pk_bf16_f32 v106, v108, v109
	s_nop 0
	v_cvt_pk_bf16_f32 v107, v110, v111
	ds_read_b32 v108, v209 offset:8384
	global_store_dwordx4 v[160:161], v[104:107], off sc1
	s_nop 1
	v_cvt_pk_bf16_f32 v104, v100, v101
	v_cvt_pk_bf16_f32 v105, v102, v103
	v_cvt_pk_bf16_f32 v106, v96, v97
	v_cvt_pk_bf16_f32 v107, v98, v99
	s_waitcnt lgkmcnt(0)
	v_pk_mul_f32 v[102:103], v[102:103], v[108:109] op_sel_hi:[1,0]
	v_pk_mul_f32 v[98:99], v[98:99], v[108:109] op_sel_hi:[1,0]
	v_pk_mul_f32 v[96:97], v[96:97], v[108:109] op_sel_hi:[1,0]
	global_store_dwordx4 v[174:175], v[104:107], off nt
	v_pk_mul_f32 v[100:101], v[100:101], v[108:109] op_sel_hi:[1,0]
	v_pk_mul_f32 v[102:103], v[242:243], v[102:103]
	v_pk_mul_f32 v[104:105], v[246:247], v[98:99]
	v_pk_mul_f32 v[98:99], v[244:245], v[96:97]
	v_pk_mul_f32 v[100:101], v[240:241], v[100:101]
	s_nop 0
	v_cvt_pk_bf16_f32 v96, v100, v101
	v_cvt_pk_bf16_f32 v97, v102, v103
	v_cvt_pk_bf16_f32 v98, v98, v99
	v_cvt_pk_bf16_f32 v99, v104, v105
	ds_read_b32 v102, v209 offset:8704
	v_lshl_add_u64 v[100:101], s[10:11], 0, v[166:167]
	global_store_dwordx4 v[100:101], v[96:99], off sc1
	s_nop 1
	v_lshlrev_b64 v[96:97], 10, v[142:143]
	v_lshl_add_u64 v[104:105], v[96:97], 0, v[200:201]
	v_lshlrev_b64 v[104:105], 1, v[104:105]
	v_cvt_pk_bf16_f32 v98, v92, v93
	v_cvt_pk_bf16_f32 v99, v94, v95
	v_cvt_pk_bf16_f32 v100, v88, v89
	v_cvt_pk_bf16_f32 v101, v90, v91
	v_lshl_add_u64 v[106:107], s[8:9], 0, v[104:105]
	s_waitcnt lgkmcnt(0)
	v_pk_mul_f32 v[94:95], v[94:95], v[102:103] op_sel_hi:[1,0]
	v_pk_mul_f32 v[90:91], v[90:91], v[102:103] op_sel_hi:[1,0]
	v_pk_mul_f32 v[88:89], v[88:89], v[102:103] op_sel_hi:[1,0]
	global_store_dwordx4 v[106:107], v[98:101], off nt
	v_pk_mul_f32 v[92:93], v[92:93], v[102:103] op_sel_hi:[1,0]
	v_pk_mul_f32 v[94:95], v[242:243], v[94:95]
	v_pk_mul_f32 v[98:99], v[246:247], v[90:91]
	v_pk_mul_f32 v[90:91], v[244:245], v[88:89]
	v_pk_mul_f32 v[92:93], v[240:241], v[92:93]
	s_nop 0
	v_cvt_pk_bf16_f32 v88, v92, v93
	v_cvt_pk_bf16_f32 v89, v94, v95
	v_cvt_pk_bf16_f32 v90, v90, v91
	v_cvt_pk_bf16_f32 v91, v98, v99
	ds_read_b32 v94, v209 offset:8768
	v_lshl_add_u64 v[92:93], s[10:11], 0, v[104:105]
	global_store_dwordx4 v[92:93], v[88:91], off sc1
	s_nop 1
	v_lshlrev_b64 v[88:89], 10, v[140:141]
	v_lshl_add_u64 v[98:99], v[88:89], 0, v[200:201]
	v_lshlrev_b64 v[98:99], 1, v[98:99]
	v_cvt_pk_bf16_f32 v90, v84, v85
	v_cvt_pk_bf16_f32 v91, v86, v87
	v_cvt_pk_bf16_f32 v92, v80, v81
	v_cvt_pk_bf16_f32 v93, v82, v83
	v_lshl_add_u64 v[100:101], s[8:9], 0, v[98:99]
	s_waitcnt lgkmcnt(0)
	v_pk_mul_f32 v[86:87], v[86:87], v[94:95] op_sel_hi:[1,0]
	v_pk_mul_f32 v[82:83], v[82:83], v[94:95] op_sel_hi:[1,0]
	v_pk_mul_f32 v[80:81], v[80:81], v[94:95] op_sel_hi:[1,0]
	global_store_dwordx4 v[100:101], v[90:93], off nt
	v_pk_mul_f32 v[84:85], v[84:85], v[94:95] op_sel_hi:[1,0]
	v_pk_mul_f32 v[86:87], v[242:243], v[86:87]
	v_pk_mul_f32 v[90:91], v[246:247], v[82:83]
	v_pk_mul_f32 v[82:83], v[244:245], v[80:81]
	v_pk_mul_f32 v[84:85], v[240:241], v[84:85]
	s_nop 0
	v_cvt_pk_bf16_f32 v80, v84, v85
	v_cvt_pk_bf16_f32 v81, v86, v87
	v_cvt_pk_bf16_f32 v82, v82, v83
	v_cvt_pk_bf16_f32 v83, v90, v91
	ds_read_b32 v86, v209 offset:8832
	v_lshl_add_u64 v[84:85], s[10:11], 0, v[98:99]
	global_store_dwordx4 v[84:85], v[80:83], off sc1
	s_nop 1
	v_lshlrev_b64 v[80:81], 10, v[138:139]
	v_lshl_add_u64 v[90:91], v[80:81], 0, v[200:201]
	v_lshlrev_b64 v[90:91], 1, v[90:91]
	v_cvt_pk_bf16_f32 v82, v76, v77
	v_cvt_pk_bf16_f32 v83, v78, v79
	v_cvt_pk_bf16_f32 v84, v72, v73
	v_cvt_pk_bf16_f32 v85, v74, v75
	v_lshl_add_u64 v[92:93], s[8:9], 0, v[90:91]
	s_waitcnt lgkmcnt(0)
	v_pk_mul_f32 v[78:79], v[78:79], v[86:87] op_sel_hi:[1,0]
	v_pk_mul_f32 v[74:75], v[74:75], v[86:87] op_sel_hi:[1,0]
	v_pk_mul_f32 v[72:73], v[72:73], v[86:87] op_sel_hi:[1,0]
	global_store_dwordx4 v[92:93], v[82:85], off nt
	v_pk_mul_f32 v[76:77], v[76:77], v[86:87] op_sel_hi:[1,0]
	v_pk_mul_f32 v[78:79], v[242:243], v[78:79]
	v_pk_mul_f32 v[82:83], v[246:247], v[74:75]
	v_pk_mul_f32 v[74:75], v[244:245], v[72:73]
	v_pk_mul_f32 v[76:77], v[240:241], v[76:77]
	s_nop 0
	v_cvt_pk_bf16_f32 v72, v76, v77
	v_cvt_pk_bf16_f32 v73, v78, v79
	v_cvt_pk_bf16_f32 v74, v74, v75
	v_cvt_pk_bf16_f32 v75, v82, v83
	ds_read_b32 v78, v209 offset:8896
	v_lshl_add_u64 v[76:77], s[10:11], 0, v[90:91]
	global_store_dwordx4 v[76:77], v[72:75], off sc1
	s_nop 1
	v_lshlrev_b64 v[72:73], 10, v[136:137]
	v_lshl_add_u64 v[82:83], v[72:73], 0, v[200:201]
	v_cvt_pk_bf16_f32 v74, v68, v69
	v_lshlrev_b64 v[82:83], 1, v[82:83]
	s_waitcnt lgkmcnt(0)
	v_pk_mul_f32 v[68:69], v[68:69], v[78:79] op_sel_hi:[1,0]
	v_cvt_pk_bf16_f32 v75, v70, v71
	v_cvt_pk_bf16_f32 v76, v64, v65
	v_cvt_pk_bf16_f32 v77, v66, v67
	v_lshl_add_u64 v[84:85], s[8:9], 0, v[82:83]
	v_pk_mul_f32 v[68:69], v[240:241], v[68:69]
	v_pk_mul_f32 v[66:67], v[66:67], v[78:79] op_sel_hi:[1,0]
	v_pk_mul_f32 v[64:65], v[64:65], v[78:79] op_sel_hi:[1,0]
	global_store_dwordx4 v[84:85], v[74:77], off nt
	v_pk_mul_f32 v[70:71], v[70:71], v[78:79] op_sel_hi:[1,0]
	v_or_b32_e32 v200, 0x80, v200
	v_pk_mul_f32 v[74:75], v[246:247], v[66:67]
	v_pk_mul_f32 v[66:67], v[244:245], v[64:65]
	v_cvt_pk_bf16_f32 v64, v68, v69
	v_lshl_add_u64 v[68:69], s[10:11], 0, v[82:83]
	v_pk_mul_f32 v[70:71], v[242:243], v[70:71]
	v_lshl_add_u64 v[82:83], v[144:145], 0, v[200:201]
	v_cvt_pk_bf16_f32 v65, v70, v71
	v_cvt_pk_bf16_f32 v66, v66, v67
	v_cvt_pk_bf16_f32 v67, v74, v75
	global_store_dwordx4 v[68:69], v[64:67], off sc1
	s_nop 0
	ds_read_b32 v78, v209 offset:8192
	v_cvt_pk_bf16_f32 v74, v60, v61
	v_lshlrev_b64 v[82:83], 1, v[82:83]
	v_cvt_pk_bf16_f32 v75, v62, v63
	v_cvt_pk_bf16_f32 v76, v56, v57
	s_waitcnt lgkmcnt(0)
	v_pk_mul_f32 v[60:61], v[60:61], v[78:79] op_sel_hi:[1,0]
	v_cvt_pk_bf16_f32 v77, v58, v59
	v_lshl_add_u64 v[84:85], s[8:9], 0, v[82:83]
	v_pk_mul_f32 v[58:59], v[58:59], v[78:79] op_sel_hi:[1,0]
	v_pk_mul_f32 v[56:57], v[56:57], v[78:79] op_sel_hi:[1,0]
	global_store_dwordx4 v[84:85], v[74:77], off nt
	v_pk_mul_f32 v[62:63], v[62:63], v[78:79] op_sel_hi:[1,0]
	v_pk_mul_f32 v[60:61], v[226:227], v[60:61]
	v_pk_mul_f32 v[74:75], v[232:233], v[58:59]
	v_pk_mul_f32 v[58:59], v[230:231], v[56:57]
	v_cvt_pk_bf16_f32 v56, v60, v61
	v_lshl_add_u64 v[60:61], s[10:11], 0, v[82:83]
	v_pk_mul_f32 v[62:63], v[228:229], v[62:63]
	s_nop 0
	v_cvt_pk_bf16_f32 v57, v62, v63
	v_cvt_pk_bf16_f32 v58, v58, v59
	v_cvt_pk_bf16_f32 v59, v74, v75
	global_store_dwordx4 v[60:61], v[56:59], off sc1
	ds_read_b32 v60, v209 offset:8256
	v_lshl_add_u64 v[62:63], v[150:151], 0, v[200:201]
	v_cvt_pk_bf16_f32 v56, v52, v53
	v_lshlrev_b64 v[62:63], 1, v[62:63]
	v_cvt_pk_bf16_f32 v57, v54, v55
	s_waitcnt lgkmcnt(0)
	v_pk_mul_f32 v[52:53], v[52:53], v[60:61] op_sel_hi:[1,0]
	v_cvt_pk_bf16_f32 v58, v48, v49
	v_cvt_pk_bf16_f32 v59, v50, v51
	v_lshl_add_u64 v[74:75], s[8:9], 0, v[62:63]
	v_pk_mul_f32 v[52:53], v[226:227], v[52:53]
	v_pk_mul_f32 v[50:51], v[50:51], v[60:61] op_sel_hi:[1,0]
	v_pk_mul_f32 v[48:49], v[48:49], v[60:61] op_sel_hi:[1,0]
	global_store_dwordx4 v[74:75], v[56:59], off nt
	v_pk_mul_f32 v[54:55], v[54:55], v[60:61] op_sel_hi:[1,0]
	s_nop 0
	v_pk_mul_f32 v[56:57], v[232:233], v[50:51]
	v_pk_mul_f32 v[50:51], v[230:231], v[48:49]
	v_cvt_pk_bf16_f32 v48, v52, v53
	v_lshl_add_u64 v[52:53], s[10:11], 0, v[62:63]
	v_pk_mul_f32 v[54:55], v[228:229], v[54:55]
	s_nop 0
	v_cvt_pk_bf16_f32 v49, v54, v55
	v_cvt_pk_bf16_f32 v50, v50, v51
	v_cvt_pk_bf16_f32 v51, v56, v57
	global_store_dwordx4 v[52:53], v[48:51], off sc1
	ds_read_b32 v52, v209 offset:8320
	v_lshl_add_u64 v[54:55], v[148:149], 0, v[200:201]
	v_cvt_pk_bf16_f32 v48, v44, v45
	v_lshlrev_b64 v[54:55], 1, v[54:55]
	v_cvt_pk_bf16_f32 v49, v46, v47
	s_waitcnt lgkmcnt(0)
	v_pk_mul_f32 v[44:45], v[44:45], v[52:53] op_sel_hi:[1,0]
	v_cvt_pk_bf16_f32 v50, v40, v41
	v_cvt_pk_bf16_f32 v51, v42, v43
	v_lshl_add_u64 v[56:57], s[8:9], 0, v[54:55]
	v_pk_mul_f32 v[44:45], v[226:227], v[44:45]
	v_pk_mul_f32 v[42:43], v[42:43], v[52:53] op_sel_hi:[1,0]
	v_pk_mul_f32 v[40:41], v[40:41], v[52:53] op_sel_hi:[1,0]
	global_store_dwordx4 v[56:57], v[48:51], off nt
	v_pk_mul_f32 v[46:47], v[46:47], v[52:53] op_sel_hi:[1,0]
	s_nop 0
	v_pk_mul_f32 v[48:49], v[232:233], v[42:43]
	v_pk_mul_f32 v[42:43], v[230:231], v[40:41]
	v_cvt_pk_bf16_f32 v40, v44, v45
	v_lshl_add_u64 v[44:45], s[10:11], 0, v[54:55]
	v_pk_mul_f32 v[46:47], v[228:229], v[46:47]
	s_nop 0
	v_cvt_pk_bf16_f32 v41, v46, v47
	v_cvt_pk_bf16_f32 v42, v42, v43
	v_cvt_pk_bf16_f32 v43, v48, v49
	global_store_dwordx4 v[44:45], v[40:43], off sc1
	ds_read_b32 v44, v209 offset:8384
	v_lshl_add_u64 v[46:47], v[146:147], 0, v[200:201]
	v_cvt_pk_bf16_f32 v40, v36, v37
	v_lshlrev_b64 v[46:47], 1, v[46:47]
	v_cvt_pk_bf16_f32 v41, v38, v39
	s_waitcnt lgkmcnt(0)
	v_pk_mul_f32 v[36:37], v[36:37], v[44:45] op_sel_hi:[1,0]
	v_cvt_pk_bf16_f32 v42, v32, v33
	v_cvt_pk_bf16_f32 v43, v34, v35
	v_lshl_add_u64 v[48:49], s[8:9], 0, v[46:47]
	v_pk_mul_f32 v[36:37], v[226:227], v[36:37]
	v_pk_mul_f32 v[34:35], v[34:35], v[44:45] op_sel_hi:[1,0]
	v_pk_mul_f32 v[32:33], v[32:33], v[44:45] op_sel_hi:[1,0]
	global_store_dwordx4 v[48:49], v[40:43], off nt
	v_pk_mul_f32 v[38:39], v[38:39], v[44:45] op_sel_hi:[1,0]
	s_nop 0
	v_pk_mul_f32 v[40:41], v[232:233], v[34:35]
	v_pk_mul_f32 v[34:35], v[230:231], v[32:33]
	v_cvt_pk_bf16_f32 v32, v36, v37
	v_lshl_add_u64 v[36:37], s[10:11], 0, v[46:47]
	v_pk_mul_f32 v[38:39], v[228:229], v[38:39]
	s_nop 0
	v_cvt_pk_bf16_f32 v33, v38, v39
	v_cvt_pk_bf16_f32 v34, v34, v35
	v_cvt_pk_bf16_f32 v35, v40, v41
	global_store_dwordx4 v[36:37], v[32:35], off sc1
	ds_read_b32 v36, v209 offset:8704
	v_lshl_add_u64 v[38:39], v[96:97], 0, v[200:201]
	v_cvt_pk_bf16_f32 v32, v28, v29
	v_lshlrev_b64 v[38:39], 1, v[38:39]
	v_cvt_pk_bf16_f32 v33, v30, v31
	s_waitcnt lgkmcnt(0)
	v_pk_mul_f32 v[28:29], v[28:29], v[36:37] op_sel_hi:[1,0]
	v_cvt_pk_bf16_f32 v34, v24, v25
	v_cvt_pk_bf16_f32 v35, v26, v27
	v_lshl_add_u64 v[40:41], s[8:9], 0, v[38:39]
	v_pk_mul_f32 v[28:29], v[226:227], v[28:29]
	v_pk_mul_f32 v[26:27], v[26:27], v[36:37] op_sel_hi:[1,0]
	v_pk_mul_f32 v[24:25], v[24:25], v[36:37] op_sel_hi:[1,0]
	global_store_dwordx4 v[40:41], v[32:35], off nt
	v_pk_mul_f32 v[30:31], v[30:31], v[36:37] op_sel_hi:[1,0]
	s_nop 0
	v_pk_mul_f32 v[32:33], v[232:233], v[26:27]
	v_pk_mul_f32 v[26:27], v[230:231], v[24:25]
	v_cvt_pk_bf16_f32 v24, v28, v29
	v_lshl_add_u64 v[28:29], s[10:11], 0, v[38:39]
	v_pk_mul_f32 v[30:31], v[228:229], v[30:31]
	s_nop 0
	v_cvt_pk_bf16_f32 v25, v30, v31
	v_cvt_pk_bf16_f32 v26, v26, v27
	v_cvt_pk_bf16_f32 v27, v32, v33
	global_store_dwordx4 v[28:29], v[24:27], off sc1
	ds_read_b32 v28, v209 offset:8768
	v_lshl_add_u64 v[30:31], v[88:89], 0, v[200:201]
	v_cvt_pk_bf16_f32 v24, v20, v21
	v_lshlrev_b64 v[30:31], 1, v[30:31]
	v_cvt_pk_bf16_f32 v25, v22, v23
	s_waitcnt lgkmcnt(0)
	v_pk_mul_f32 v[20:21], v[20:21], v[28:29] op_sel_hi:[1,0]
	v_cvt_pk_bf16_f32 v26, v16, v17
	v_cvt_pk_bf16_f32 v27, v18, v19
	v_lshl_add_u64 v[32:33], s[8:9], 0, v[30:31]
	v_pk_mul_f32 v[20:21], v[226:227], v[20:21]
	v_pk_mul_f32 v[18:19], v[18:19], v[28:29] op_sel_hi:[1,0]
	v_pk_mul_f32 v[16:17], v[16:17], v[28:29] op_sel_hi:[1,0]
	global_store_dwordx4 v[32:33], v[24:27], off nt
	v_pk_mul_f32 v[22:23], v[22:23], v[28:29] op_sel_hi:[1,0]
	s_nop 0
	v_pk_mul_f32 v[24:25], v[232:233], v[18:19]
	v_pk_mul_f32 v[18:19], v[230:231], v[16:17]
	v_cvt_pk_bf16_f32 v16, v20, v21
	v_lshl_add_u64 v[20:21], s[10:11], 0, v[30:31]
	v_pk_mul_f32 v[22:23], v[228:229], v[22:23]
	s_nop 0
	v_cvt_pk_bf16_f32 v17, v22, v23
	v_cvt_pk_bf16_f32 v18, v18, v19
	v_cvt_pk_bf16_f32 v19, v24, v25
	global_store_dwordx4 v[20:21], v[16:19], off sc1
	ds_read_b32 v20, v209 offset:8832
	v_lshl_add_u64 v[22:23], v[80:81], 0, v[200:201]
	v_cvt_pk_bf16_f32 v16, v12, v13
	v_lshlrev_b64 v[22:23], 1, v[22:23]
	v_cvt_pk_bf16_f32 v17, v14, v15
	s_waitcnt lgkmcnt(0)
	v_pk_mul_f32 v[12:13], v[12:13], v[20:21] op_sel_hi:[1,0]
	v_cvt_pk_bf16_f32 v18, v8, v9
	v_cvt_pk_bf16_f32 v19, v10, v11
	v_lshl_add_u64 v[24:25], s[8:9], 0, v[22:23]
	v_pk_mul_f32 v[12:13], v[226:227], v[12:13]
	v_pk_mul_f32 v[10:11], v[10:11], v[20:21] op_sel_hi:[1,0]
	v_pk_mul_f32 v[8:9], v[8:9], v[20:21] op_sel_hi:[1,0]
	global_store_dwordx4 v[24:25], v[16:19], off nt
	v_pk_mul_f32 v[14:15], v[14:15], v[20:21] op_sel_hi:[1,0]
	s_nop 0
	v_pk_mul_f32 v[16:17], v[232:233], v[10:11]
	v_pk_mul_f32 v[10:11], v[230:231], v[8:9]
	v_cvt_pk_bf16_f32 v8, v12, v13
	v_lshl_add_u64 v[12:13], s[10:11], 0, v[22:23]
	v_pk_mul_f32 v[14:15], v[228:229], v[14:15]
	s_nop 0
	v_cvt_pk_bf16_f32 v9, v14, v15
	v_cvt_pk_bf16_f32 v10, v10, v11
	v_cvt_pk_bf16_f32 v11, v16, v17
	global_store_dwordx4 v[12:13], v[8:11], off sc1
	ds_read_b32 v12, v209 offset:8896
	v_lshl_add_u64 v[14:15], v[72:73], 0, v[200:201]
	v_cvt_pk_bf16_f32 v8, v4, v5
	v_lshlrev_b64 v[14:15], 1, v[14:15]
	v_cvt_pk_bf16_f32 v9, v6, v7
	s_waitcnt lgkmcnt(0)
	v_pk_mul_f32 v[4:5], v[4:5], v[12:13] op_sel_hi:[1,0]
	v_cvt_pk_bf16_f32 v10, v0, v1
	v_cvt_pk_bf16_f32 v11, v2, v3
	v_lshl_add_u64 v[16:17], s[8:9], 0, v[14:15]
	v_pk_mul_f32 v[4:5], v[226:227], v[4:5]
	v_pk_mul_f32 v[2:3], v[2:3], v[12:13] op_sel_hi:[1,0]
	v_pk_mul_f32 v[0:1], v[0:1], v[12:13] op_sel_hi:[1,0]
	global_store_dwordx4 v[16:17], v[8:11], off nt
	v_pk_mul_f32 v[6:7], v[6:7], v[12:13] op_sel_hi:[1,0]
	s_nop 0
	v_pk_mul_f32 v[8:9], v[232:233], v[2:3]
	v_pk_mul_f32 v[2:3], v[230:231], v[0:1]
	v_cvt_pk_bf16_f32 v0, v4, v5
	v_lshl_add_u64 v[4:5], s[10:11], 0, v[14:15]
	v_pk_mul_f32 v[6:7], v[228:229], v[6:7]
	s_nop 0
	v_cvt_pk_bf16_f32 v1, v6, v7
	v_cvt_pk_bf16_f32 v2, v2, v3
	v_cvt_pk_bf16_f32 v3, v8, v9
	global_store_dwordx4 v[4:5], v[0:3], off sc1

.LBB0_774:
	s_and_b32 s16, s12, -16
	s_nop 1
	v_or_b32_e32 v10, s16, v0
	v_ashrrev_i32_e32 v11, 31, v10
	s_and_b32 s17, s15, 3
	v_lshlrev_b64 v[42:43], 11, v[10:11]
	s_lshl_b32 s10, s17, 9
	v_lshl_add_u64 v[42:43], s[44:45], 0, v[42:43]
	v_lshl_add_u64 v[42:43], v[42:43], 0, s[10:11]
	v_lshl_add_u64 v[38:39], v[4:5], 0, s[10:11]
	v_lshl_add_u64 v[70:71], v[42:43], 0, v[6:7]
	global_load_dwordx4 v[10:13], v[38:39], off
	global_load_dwordx4 v[14:17], v[38:39], off offset:64
	global_load_dwordx4 v[18:21], v[38:39], off offset:128
	global_load_dwordx4 v[22:25], v[38:39], off offset:192
	global_load_dwordx4 v[26:29], v[38:39], off offset:256
	global_load_dwordx4 v[30:33], v[38:39], off offset:320
	global_load_dwordx4 v[34:37], v[38:39], off offset:384
	s_nop 0
	global_load_dwordx4 v[38:41], v[38:39], off offset:448
	s_nop 0
	global_load_dwordx4 v[42:45], v[70:71], off
	global_load_dwordx4 v[46:49], v[70:71], off offset:64
	global_load_dwordx4 v[50:53], v[70:71], off offset:128
	global_load_dwordx4 v[54:57], v[70:71], off offset:192
	global_load_dwordx4 v[58:61], v[70:71], off offset:256
	global_load_dwordx4 v[62:65], v[70:71], off offset:320
	global_load_dwordx4 v[66:69], v[70:71], off offset:384
	v_lshl_add_u32 v2, s17, 7, v1
	s_ashr_i32 s17, s16, 31
	s_add_i32 s15, s15, s33
	s_add_i32 s12, s12, s13
	s_cmpk_gt_i32 s15, 0xff
	s_waitcnt vmcnt(6)
	v_mfma_f32_16x16x32_bf16 v[10:13], v[10:13], v[42:45], 0
	global_load_dwordx4 v[42:45], v[70:71], off offset:448
	s_waitcnt vmcnt(6)
	v_mfma_f32_16x16x32_bf16 v[10:13], v[14:17], v[46:49], v[10:13]
	v_lshlrev_b64 v[14:15], 12, v[2:3]
	v_lshl_add_u64 v[14:15], s[8:9], 0, v[14:15]
	v_lshl_add_u64 v[14:15], s[16:17], 2, v[14:15]
	s_waitcnt vmcnt(5)
	v_mfma_f32_16x16x32_bf16 v[10:13], v[18:21], v[50:53], v[10:13]
	v_lshl_add_u64 v[14:15], v[14:15], 0, v[8:9]
	v_add_co_u32_e32 v16, vcc, s14, v14
	s_waitcnt vmcnt(4)
	v_mfma_f32_16x16x32_bf16 v[10:13], v[22:25], v[54:57], v[10:13]
	v_addc_co_u32_e32 v17, vcc, 0, v15, vcc
	v_add_co_u32_e32 v18, vcc, 0x2000, v14
	s_waitcnt vmcnt(3)
	v_mfma_f32_16x16x32_bf16 v[10:13], v[26:29], v[58:61], v[10:13]
	v_addc_co_u32_e32 v19, vcc, 0, v15, vcc
	v_add_co_u32_e32 v20, vcc, 0x3000, v14
	s_waitcnt vmcnt(2)
	v_mfma_f32_16x16x32_bf16 v[10:13], v[30:33], v[62:65], v[10:13]
	v_addc_co_u32_e32 v21, vcc, 0, v15, vcc
	s_waitcnt vmcnt(1)
	v_mfma_f32_16x16x32_bf16 v[10:13], v[34:37], v[66:69], v[10:13]
	s_waitcnt vmcnt(0)
	v_mfma_f32_16x16x32_bf16 v[10:13], v[38:41], v[42:45], v[10:13]
	s_nop 7
	global_store_dword v[14:15], v10, off sc1
	global_store_dword v[16:17], v11, off sc1
	global_store_dword v[18:19], v12, off sc1
	global_store_dword v[20:21], v13, off sc1
	s_cbranch_scc0 .LBB0_774
.LBB0_775:
	s_waitcnt vmcnt(0)
	s_and_b64 vcc, exec, s[94:95]
	s_barrier
	s_cbranch_vccnz .LBB0_829
	v_mbcnt_lo_u32_b32 v0, -1, 0
	v_mbcnt_hi_u32_b32 v0, -1, v0
	s_nop 0
	v_cmp_eq_u32_e32 vcc, 0, v0
	s_and_saveexec_b64 s[8:9], vcc
	s_cbranch_execz .LBB0_828
	s_and_b32 s10, s2, 7
	s_lshl_b32 s10, s10, 3
	s_bfe_u32 s11, s2, 0x30003
	s_or_b32 s10, s10, s11
	s_lshl_b32 s10, s10, 8
	s_add_u32 s12, s0, 0x14000
	s_addc_u32 s13, s1, 0
	s_add_u32 s12, s12, s10
	s_addc_u32 s13, s13, 0
	s_add_u32 s14, s0, 0x28500
	s_addc_u32 s15, s1, 0
	v_mov_b32_e32 v0, 0
	v_mov_b32_e32 v1, 1
	s_waitcnt vmcnt(0) lgkmcnt(0)
	global_atomic_add v0, v1, s[12:13]
	global_atomic_add v0, v1, s[14:15]
	s_mov_b32 s16, 0

.LBB0_1005:
	s_waitcnt vmcnt(0)
	v_readlane_b32 s4, v248, 5
	v_readlane_b32 s5, v248, 6
	s_and_b64 vcc, exec, s[4:5]
	s_barrier
	s_cbranch_vccz .LBB0_1059
	v_mbcnt_lo_u32_b32 v0, -1, 0
	v_mbcnt_hi_u32_b32 v0, -1, v0
	s_nop 0
	v_cmp_eq_u32_e32 vcc, 0, v0
	s_and_saveexec_b64 s[4:5], vcc
	s_cbranch_execz .LBB0_1058
	s_and_b32 s10, s2, 7
	s_lshl_b32 s10, s10, 3
	s_bfe_u32 s11, s2, 0x30003
	s_or_b32 s10, s10, s11
	s_lshl_b32 s10, s10, 8
	s_add_u32 s12, s0, 0x29000
	s_addc_u32 s13, s1, 0
	s_add_u32 s12, s12, s10
	s_addc_u32 s13, s13, 0
	s_add_u32 s14, s0, 0x28400
	s_addc_u32 s15, s1, 0
	v_mov_b32_e32 v0, 0
	v_mov_b32_e32 v1, 1
	s_waitcnt vmcnt(0) lgkmcnt(0)
	global_atomic_add v0, v1, s[12:13]
	global_atomic_add v0, v1, s[14:15]
	s_mov_b32 s16, 0

.Lr9_panel_ok:
	s_and_b32 s17, s92, 15
	s_cmp_eq_u32 s17, 2
	s_cbranch_scc0 .Lr9_acq
	s_mov_b32 s16, 0
